# all three EpiResid epilogues (early w_o, mixer resid, FF2) de-serialised: 16 loads in flight, batched bpermutes
# speedup vs baseline: 1.0018x; 1.0018x over previous
.LBB0_1632:
	v_lshl_add_u32 v142, s2, 8, v144
	v_ashrrev_i32_e32 v143, 31, v142
	v_lshl_or_b32 v140, s9, 8, v146
	v_lshlrev_b32_e32 v141, 12, v142
	v_lshl_add_u32 v141, v140, 1, v141
	global_load_dwordx4 v[148:151], v141, s[22:23]
	global_load_dwordx4 v[152:155], v141, s[22:23] offset:256
	s_add_u32 s56, s22, 0x10000
	s_addc_u32 s57, s23, 0
	global_load_dwordx4 v[168:171], v141, s[56:57]
	global_load_dwordx4 v[172:175], v141, s[56:57] offset:256
	s_add_u32 s56, s22, 0x20000
	s_addc_u32 s57, s23, 0
	global_load_dwordx4 v[180:183], v141, s[56:57]
	global_load_dwordx4 v[184:187], v141, s[56:57] offset:256
	s_add_u32 s56, s22, 0x30000
	s_addc_u32 s57, s23, 0
	global_load_dwordx4 v[188:191], v141, s[56:57]
	global_load_dwordx4 v[192:195], v141, s[56:57] offset:256
	s_add_u32 s56, s22, 0x80000
	s_addc_u32 s57, s23, 0
	global_load_dwordx4 v[196:199], v141, s[56:57]
	global_load_dwordx4 v[200:203], v141, s[56:57] offset:256
	s_add_u32 s56, s22, 0x90000
	s_addc_u32 s57, s23, 0
	global_load_dwordx4 v[204:207], v141, s[56:57]
	global_load_dwordx4 v[214:217], v141, s[56:57] offset:256
	s_add_u32 s56, s22, 0xa0000
	s_addc_u32 s57, s23, 0
	global_load_dwordx4 v[230:233], v141, s[56:57]
	global_load_dwordx4 v[234:237], v141, s[56:57] offset:256
	s_add_u32 s56, s22, 0xb0000
	s_addc_u32 s57, s23, 0
	global_load_dwordx4 v[238:241], v141, s[56:57]
	global_load_dwordx4 v[242:245], v141, s[56:57] offset:256
	v_xor_b32_e32 v178, 16, v1
	v_xor_b32_e32 v208, 32, v1
	v_lshlrev_b32_e32 v178, 2, v178
	v_lshlrev_b32_e32 v208, 2, v208
	v_lshlrev_b32_e32 v209, 7, v142
	s_waitcnt vmcnt(15)
	v_lshlrev_b32_e32 v156, 16, v148
	v_and_b32_e32 v148, 0xffff0000, v148
	v_lshlrev_b32_e32 v157, 16, v149
	v_and_b32_e32 v149, 0xffff0000, v149
	v_lshlrev_b32_e32 v176, 16, v150
	v_and_b32_e32 v150, 0xffff0000, v150
	v_lshlrev_b32_e32 v177, 16, v151
	v_and_b32_e32 v151, 0xffff0000, v151
	v_add_f32_e32 v126, v126, v156
	v_add_f32_e32 v127, v127, v148
	v_add_f32_e32 v128, v128, v157
	v_add_f32_e32 v129, v129, v149
	v_add_f32_e32 v122, v122, v176
	v_add_f32_e32 v123, v123, v150
	v_add_f32_e32 v124, v124, v177
	v_add_f32_e32 v125, v125, v151
	v_cvt_pk_bf16_f32 v148, v126, v127
	v_cvt_pk_bf16_f32 v149, v128, v129
	v_cvt_pk_bf16_f32 v150, v122, v123
	v_cvt_pk_bf16_f32 v151, v124, v125
	global_store_dwordx4 v141, v[148:151], s[22:23]
	v_mul_f32_e32 v156, v127, v127
	v_mul_f32_e32 v157, v129, v129
	v_fmac_f32_e32 v156, v126, v126
	v_fmac_f32_e32 v157, v128, v128
	v_add_f32_e32 v156, v156, v157
	v_mul_f32_e32 v176, v123, v123
	v_mul_f32_e32 v177, v125, v125
	v_fmac_f32_e32 v176, v122, v122
	v_fmac_f32_e32 v177, v124, v124
	v_add_f32_e32 v176, v176, v177
	v_add_f32_e32 v126, v156, v176
	s_waitcnt vmcnt(15)
	v_lshlrev_b32_e32 v156, 16, v152
	v_and_b32_e32 v152, 0xffff0000, v152
	v_lshlrev_b32_e32 v157, 16, v153
	v_and_b32_e32 v153, 0xffff0000, v153
	v_lshlrev_b32_e32 v176, 16, v154
	v_and_b32_e32 v154, 0xffff0000, v154
	v_lshlrev_b32_e32 v177, 16, v155
	v_and_b32_e32 v155, 0xffff0000, v155
	v_add_f32_e32 v118, v118, v156
	v_add_f32_e32 v119, v119, v152
	v_add_f32_e32 v120, v120, v157
	v_add_f32_e32 v121, v121, v153
	v_add_f32_e32 v114, v114, v176
	v_add_f32_e32 v115, v115, v154
	v_add_f32_e32 v116, v116, v177
	v_add_f32_e32 v117, v117, v155
	v_cvt_pk_bf16_f32 v152, v118, v119
	v_cvt_pk_bf16_f32 v153, v120, v121
	v_cvt_pk_bf16_f32 v154, v114, v115
	v_cvt_pk_bf16_f32 v155, v116, v117
	global_store_dwordx4 v141, v[152:155], s[22:23] offset:256
	v_mul_f32_e32 v156, v119, v119
	v_mul_f32_e32 v157, v121, v121
	v_fmac_f32_e32 v156, v118, v118
	v_fmac_f32_e32 v157, v120, v120
	v_add_f32_e32 v156, v156, v157
	v_mul_f32_e32 v176, v115, v115
	v_mul_f32_e32 v177, v117, v117
	v_fmac_f32_e32 v176, v114, v114
	v_fmac_f32_e32 v177, v116, v116
	v_add_f32_e32 v176, v176, v177
	v_add_f32_e32 v156, v156, v176
	v_add_f32_e32 v126, v126, v156
	s_add_u32 s56, s22, 0x10000
	s_addc_u32 s57, s23, 0
	s_waitcnt vmcnt(15)
	v_lshlrev_b32_e32 v156, 16, v168
	v_and_b32_e32 v168, 0xffff0000, v168
	v_lshlrev_b32_e32 v157, 16, v169
	v_and_b32_e32 v169, 0xffff0000, v169
	v_lshlrev_b32_e32 v176, 16, v170
	v_and_b32_e32 v170, 0xffff0000, v170
	v_lshlrev_b32_e32 v177, 16, v171
	v_and_b32_e32 v171, 0xffff0000, v171
	v_add_f32_e32 v110, v110, v156
	v_add_f32_e32 v111, v111, v168
	v_add_f32_e32 v112, v112, v157
	v_add_f32_e32 v113, v113, v169
	v_add_f32_e32 v106, v106, v176
	v_add_f32_e32 v107, v107, v170
	v_add_f32_e32 v108, v108, v177
	v_add_f32_e32 v109, v109, v171
	v_cvt_pk_bf16_f32 v168, v110, v111
	v_cvt_pk_bf16_f32 v169, v112, v113
	v_cvt_pk_bf16_f32 v170, v106, v107
	v_cvt_pk_bf16_f32 v171, v108, v109
	global_store_dwordx4 v141, v[168:171], s[56:57]
	v_mul_f32_e32 v156, v111, v111
	v_mul_f32_e32 v157, v113, v113
	v_fmac_f32_e32 v156, v110, v110
	v_fmac_f32_e32 v157, v112, v112
	v_add_f32_e32 v156, v156, v157
	v_mul_f32_e32 v176, v107, v107
	v_mul_f32_e32 v177, v109, v109
	v_fmac_f32_e32 v176, v106, v106
	v_fmac_f32_e32 v177, v108, v108
	v_add_f32_e32 v176, v176, v177
	v_add_f32_e32 v110, v156, v176
	s_waitcnt vmcnt(15)
	v_lshlrev_b32_e32 v156, 16, v172
	v_and_b32_e32 v172, 0xffff0000, v172
	v_lshlrev_b32_e32 v157, 16, v173
	v_and_b32_e32 v173, 0xffff0000, v173
	v_lshlrev_b32_e32 v176, 16, v174
	v_and_b32_e32 v174, 0xffff0000, v174
	v_lshlrev_b32_e32 v177, 16, v175
	v_and_b32_e32 v175, 0xffff0000, v175
	v_add_f32_e32 v102, v102, v156
	v_add_f32_e32 v103, v103, v172
	v_add_f32_e32 v104, v104, v157
	v_add_f32_e32 v105, v105, v173
	v_add_f32_e32 v98, v98, v176
	v_add_f32_e32 v99, v99, v174
	v_add_f32_e32 v100, v100, v177
	v_add_f32_e32 v101, v101, v175
	v_cvt_pk_bf16_f32 v172, v102, v103
	v_cvt_pk_bf16_f32 v173, v104, v105
	v_cvt_pk_bf16_f32 v174, v98, v99
	v_cvt_pk_bf16_f32 v175, v100, v101
	global_store_dwordx4 v141, v[172:175], s[56:57] offset:256
	v_mul_f32_e32 v156, v103, v103
	v_mul_f32_e32 v157, v105, v105
	v_fmac_f32_e32 v156, v102, v102
	v_fmac_f32_e32 v157, v104, v104
	v_add_f32_e32 v156, v156, v157
	v_mul_f32_e32 v176, v99, v99
	v_mul_f32_e32 v177, v101, v101
	v_fmac_f32_e32 v176, v98, v98
	v_fmac_f32_e32 v177, v100, v100
	v_add_f32_e32 v176, v176, v177
	v_add_f32_e32 v156, v156, v176
	v_add_f32_e32 v110, v110, v156
	s_add_u32 s56, s22, 0x20000
	s_addc_u32 s57, s23, 0
	s_waitcnt vmcnt(15)
	v_lshlrev_b32_e32 v156, 16, v180
	v_and_b32_e32 v180, 0xffff0000, v180
	v_lshlrev_b32_e32 v157, 16, v181
	v_and_b32_e32 v181, 0xffff0000, v181
	v_lshlrev_b32_e32 v176, 16, v182
	v_and_b32_e32 v182, 0xffff0000, v182
	v_lshlrev_b32_e32 v177, 16, v183
	v_and_b32_e32 v183, 0xffff0000, v183
	v_add_f32_e32 v94, v94, v156
	v_add_f32_e32 v95, v95, v180
	v_add_f32_e32 v96, v96, v157
	v_add_f32_e32 v97, v97, v181
	v_add_f32_e32 v90, v90, v176
	v_add_f32_e32 v91, v91, v182
	v_add_f32_e32 v92, v92, v177
	v_add_f32_e32 v93, v93, v183
	v_cvt_pk_bf16_f32 v180, v94, v95
	v_cvt_pk_bf16_f32 v181, v96, v97
	v_cvt_pk_bf16_f32 v182, v90, v91
	v_cvt_pk_bf16_f32 v183, v92, v93
	global_store_dwordx4 v141, v[180:183], s[56:57]
	v_mul_f32_e32 v156, v95, v95
	v_mul_f32_e32 v157, v97, v97
	v_fmac_f32_e32 v156, v94, v94
	v_fmac_f32_e32 v157, v96, v96
	v_add_f32_e32 v156, v156, v157
	v_mul_f32_e32 v176, v91, v91
	v_mul_f32_e32 v177, v93, v93
	v_fmac_f32_e32 v176, v90, v90
	v_fmac_f32_e32 v177, v92, v92
	v_add_f32_e32 v176, v176, v177
	v_add_f32_e32 v94, v156, v176
	s_waitcnt vmcnt(15)
	v_lshlrev_b32_e32 v156, 16, v184
	v_and_b32_e32 v184, 0xffff0000, v184
	v_lshlrev_b32_e32 v157, 16, v185
	v_and_b32_e32 v185, 0xffff0000, v185
	v_lshlrev_b32_e32 v176, 16, v186
	v_and_b32_e32 v186, 0xffff0000, v186
	v_lshlrev_b32_e32 v177, 16, v187
	v_and_b32_e32 v187, 0xffff0000, v187
	v_add_f32_e32 v86, v86, v156
	v_add_f32_e32 v87, v87, v184
	v_add_f32_e32 v88, v88, v157
	v_add_f32_e32 v89, v89, v185
	v_add_f32_e32 v82, v82, v176
	v_add_f32_e32 v83, v83, v186
	v_add_f32_e32 v84, v84, v177
	v_add_f32_e32 v85, v85, v187
	v_cvt_pk_bf16_f32 v184, v86, v87
	v_cvt_pk_bf16_f32 v185, v88, v89
	v_cvt_pk_bf16_f32 v186, v82, v83
	v_cvt_pk_bf16_f32 v187, v84, v85
	global_store_dwordx4 v141, v[184:187], s[56:57] offset:256
	v_mul_f32_e32 v156, v87, v87
	v_mul_f32_e32 v157, v89, v89
	v_fmac_f32_e32 v156, v86, v86
	v_fmac_f32_e32 v157, v88, v88
	v_add_f32_e32 v156, v156, v157
	v_mul_f32_e32 v176, v83, v83
	v_mul_f32_e32 v177, v85, v85
	v_fmac_f32_e32 v176, v82, v82
	v_fmac_f32_e32 v177, v84, v84
	v_add_f32_e32 v176, v176, v177
	v_add_f32_e32 v156, v156, v176
	v_add_f32_e32 v94, v94, v156
	s_add_u32 s56, s22, 0x30000
	s_addc_u32 s57, s23, 0
	s_waitcnt vmcnt(15)
	v_lshlrev_b32_e32 v156, 16, v188
	v_and_b32_e32 v188, 0xffff0000, v188
	v_lshlrev_b32_e32 v157, 16, v189
	v_and_b32_e32 v189, 0xffff0000, v189
	v_lshlrev_b32_e32 v176, 16, v190
	v_and_b32_e32 v190, 0xffff0000, v190
	v_lshlrev_b32_e32 v177, 16, v191
	v_and_b32_e32 v191, 0xffff0000, v191
	v_add_f32_e32 v78, v78, v156
	v_add_f32_e32 v79, v79, v188
	v_add_f32_e32 v80, v80, v157
	v_add_f32_e32 v81, v81, v189
	v_add_f32_e32 v74, v74, v176
	v_add_f32_e32 v75, v75, v190
	v_add_f32_e32 v76, v76, v177
	v_add_f32_e32 v77, v77, v191
	v_cvt_pk_bf16_f32 v188, v78, v79
	v_cvt_pk_bf16_f32 v189, v80, v81
	v_cvt_pk_bf16_f32 v190, v74, v75
	v_cvt_pk_bf16_f32 v191, v76, v77
	global_store_dwordx4 v141, v[188:191], s[56:57]
	v_mul_f32_e32 v156, v79, v79
	v_mul_f32_e32 v157, v81, v81
	v_fmac_f32_e32 v156, v78, v78
	v_fmac_f32_e32 v157, v80, v80
	v_add_f32_e32 v156, v156, v157
	v_mul_f32_e32 v176, v75, v75
	v_mul_f32_e32 v177, v77, v77
	v_fmac_f32_e32 v176, v74, v74
	v_fmac_f32_e32 v177, v76, v76
	v_add_f32_e32 v176, v176, v177
	v_add_f32_e32 v78, v156, v176
	s_waitcnt vmcnt(15)
	v_lshlrev_b32_e32 v156, 16, v192
	v_and_b32_e32 v192, 0xffff0000, v192
	v_lshlrev_b32_e32 v157, 16, v193
	v_and_b32_e32 v193, 0xffff0000, v193
	v_lshlrev_b32_e32 v176, 16, v194
	v_and_b32_e32 v194, 0xffff0000, v194
	v_lshlrev_b32_e32 v177, 16, v195
	v_and_b32_e32 v195, 0xffff0000, v195
	v_add_f32_e32 v70, v70, v156
	v_add_f32_e32 v71, v71, v192
	v_add_f32_e32 v72, v72, v157
	v_add_f32_e32 v73, v73, v193
	v_add_f32_e32 v66, v66, v176
	v_add_f32_e32 v67, v67, v194
	v_add_f32_e32 v68, v68, v177
	v_add_f32_e32 v69, v69, v195
	v_cvt_pk_bf16_f32 v192, v70, v71
	v_cvt_pk_bf16_f32 v193, v72, v73
	v_cvt_pk_bf16_f32 v194, v66, v67
	v_cvt_pk_bf16_f32 v195, v68, v69
	global_store_dwordx4 v141, v[192:195], s[56:57] offset:256
	v_mul_f32_e32 v156, v71, v71
	v_mul_f32_e32 v157, v73, v73
	v_fmac_f32_e32 v156, v70, v70
	v_fmac_f32_e32 v157, v72, v72
	v_add_f32_e32 v156, v156, v157
	v_mul_f32_e32 v176, v67, v67
	v_mul_f32_e32 v177, v69, v69
	v_fmac_f32_e32 v176, v66, v66
	v_fmac_f32_e32 v177, v68, v68
	v_add_f32_e32 v176, v176, v177
	v_add_f32_e32 v156, v156, v176
	v_add_f32_e32 v78, v78, v156
	s_add_u32 s56, s22, 0x80000
	s_addc_u32 s57, s23, 0
	s_waitcnt vmcnt(15)
	v_lshlrev_b32_e32 v156, 16, v196
	v_and_b32_e32 v196, 0xffff0000, v196
	v_lshlrev_b32_e32 v157, 16, v197
	v_and_b32_e32 v197, 0xffff0000, v197
	v_lshlrev_b32_e32 v176, 16, v198
	v_and_b32_e32 v198, 0xffff0000, v198
	v_lshlrev_b32_e32 v177, 16, v199
	v_and_b32_e32 v199, 0xffff0000, v199
	v_add_f32_e32 v62, v62, v156
	v_add_f32_e32 v63, v63, v196
	v_add_f32_e32 v64, v64, v157
	v_add_f32_e32 v65, v65, v197
	v_add_f32_e32 v58, v58, v176
	v_add_f32_e32 v59, v59, v198
	v_add_f32_e32 v60, v60, v177
	v_add_f32_e32 v61, v61, v199
	v_cvt_pk_bf16_f32 v196, v62, v63
	v_cvt_pk_bf16_f32 v197, v64, v65
	v_cvt_pk_bf16_f32 v198, v58, v59
	v_cvt_pk_bf16_f32 v199, v60, v61
	global_store_dwordx4 v141, v[196:199], s[56:57]
	v_mul_f32_e32 v156, v63, v63
	v_mul_f32_e32 v157, v65, v65
	v_fmac_f32_e32 v156, v62, v62
	v_fmac_f32_e32 v157, v64, v64
	v_add_f32_e32 v156, v156, v157
	v_mul_f32_e32 v176, v59, v59
	v_mul_f32_e32 v177, v61, v61
	v_fmac_f32_e32 v176, v58, v58
	v_fmac_f32_e32 v177, v60, v60
	v_add_f32_e32 v176, v176, v177
	v_add_f32_e32 v62, v156, v176
	s_waitcnt vmcnt(15)
	v_lshlrev_b32_e32 v156, 16, v200
	v_and_b32_e32 v200, 0xffff0000, v200
	v_lshlrev_b32_e32 v157, 16, v201
	v_and_b32_e32 v201, 0xffff0000, v201
	v_lshlrev_b32_e32 v176, 16, v202
	v_and_b32_e32 v202, 0xffff0000, v202
	v_lshlrev_b32_e32 v177, 16, v203
	v_and_b32_e32 v203, 0xffff0000, v203
	v_add_f32_e32 v54, v54, v156
	v_add_f32_e32 v55, v55, v200
	v_add_f32_e32 v56, v56, v157
	v_add_f32_e32 v57, v57, v201
	v_add_f32_e32 v50, v50, v176
	v_add_f32_e32 v51, v51, v202
	v_add_f32_e32 v52, v52, v177
	v_add_f32_e32 v53, v53, v203
	v_cvt_pk_bf16_f32 v200, v54, v55
	v_cvt_pk_bf16_f32 v201, v56, v57
	v_cvt_pk_bf16_f32 v202, v50, v51
	v_cvt_pk_bf16_f32 v203, v52, v53
	global_store_dwordx4 v141, v[200:203], s[56:57] offset:256
	v_mul_f32_e32 v156, v55, v55
	v_mul_f32_e32 v157, v57, v57
	v_fmac_f32_e32 v156, v54, v54
	v_fmac_f32_e32 v157, v56, v56
	v_add_f32_e32 v156, v156, v157
	v_mul_f32_e32 v176, v51, v51
	v_mul_f32_e32 v177, v53, v53
	v_fmac_f32_e32 v176, v50, v50
	v_fmac_f32_e32 v177, v52, v52
	v_add_f32_e32 v176, v176, v177
	v_add_f32_e32 v156, v156, v176
	v_add_f32_e32 v62, v62, v156
	s_add_u32 s56, s22, 0x90000
	s_addc_u32 s57, s23, 0
	s_waitcnt vmcnt(15)
	v_lshlrev_b32_e32 v156, 16, v204
	v_and_b32_e32 v204, 0xffff0000, v204
	v_lshlrev_b32_e32 v157, 16, v205
	v_and_b32_e32 v205, 0xffff0000, v205
	v_lshlrev_b32_e32 v176, 16, v206
	v_and_b32_e32 v206, 0xffff0000, v206
	v_lshlrev_b32_e32 v177, 16, v207
	v_and_b32_e32 v207, 0xffff0000, v207
	v_add_f32_e32 v46, v46, v156
	v_add_f32_e32 v47, v47, v204
	v_add_f32_e32 v48, v48, v157
	v_add_f32_e32 v49, v49, v205
	v_add_f32_e32 v42, v42, v176
	v_add_f32_e32 v43, v43, v206
	v_add_f32_e32 v44, v44, v177
	v_add_f32_e32 v45, v45, v207
	v_cvt_pk_bf16_f32 v204, v46, v47
	v_cvt_pk_bf16_f32 v205, v48, v49
	v_cvt_pk_bf16_f32 v206, v42, v43
	v_cvt_pk_bf16_f32 v207, v44, v45
	global_store_dwordx4 v141, v[204:207], s[56:57]
	v_mul_f32_e32 v156, v47, v47
	v_mul_f32_e32 v157, v49, v49
	v_fmac_f32_e32 v156, v46, v46
	v_fmac_f32_e32 v157, v48, v48
	v_add_f32_e32 v156, v156, v157
	v_mul_f32_e32 v176, v43, v43
	v_mul_f32_e32 v177, v45, v45
	v_fmac_f32_e32 v176, v42, v42
	v_fmac_f32_e32 v177, v44, v44
	v_add_f32_e32 v176, v176, v177
	v_add_f32_e32 v46, v156, v176
	s_waitcnt vmcnt(15)
	v_lshlrev_b32_e32 v156, 16, v214
	v_and_b32_e32 v214, 0xffff0000, v214
	v_lshlrev_b32_e32 v157, 16, v215
	v_and_b32_e32 v215, 0xffff0000, v215
	v_lshlrev_b32_e32 v176, 16, v216
	v_and_b32_e32 v216, 0xffff0000, v216
	v_lshlrev_b32_e32 v177, 16, v217
	v_and_b32_e32 v217, 0xffff0000, v217
	v_add_f32_e32 v38, v38, v156
	v_add_f32_e32 v39, v39, v214
	v_add_f32_e32 v40, v40, v157
	v_add_f32_e32 v41, v41, v215
	v_add_f32_e32 v34, v34, v176
	v_add_f32_e32 v35, v35, v216
	v_add_f32_e32 v36, v36, v177
	v_add_f32_e32 v37, v37, v217
	v_cvt_pk_bf16_f32 v214, v38, v39
	v_cvt_pk_bf16_f32 v215, v40, v41
	v_cvt_pk_bf16_f32 v216, v34, v35
	v_cvt_pk_bf16_f32 v217, v36, v37
	global_store_dwordx4 v141, v[214:217], s[56:57] offset:256
	v_mul_f32_e32 v156, v39, v39
	v_mul_f32_e32 v157, v41, v41
	v_fmac_f32_e32 v156, v38, v38
	v_fmac_f32_e32 v157, v40, v40
	v_add_f32_e32 v156, v156, v157
	v_mul_f32_e32 v176, v35, v35
	v_mul_f32_e32 v177, v37, v37
	v_fmac_f32_e32 v176, v34, v34
	v_fmac_f32_e32 v177, v36, v36
	v_add_f32_e32 v176, v176, v177
	v_add_f32_e32 v156, v156, v176
	v_add_f32_e32 v46, v46, v156
	s_add_u32 s56, s22, 0xa0000
	s_addc_u32 s57, s23, 0
	s_waitcnt vmcnt(15)
	v_lshlrev_b32_e32 v156, 16, v230
	v_and_b32_e32 v230, 0xffff0000, v230
	v_lshlrev_b32_e32 v157, 16, v231
	v_and_b32_e32 v231, 0xffff0000, v231
	v_lshlrev_b32_e32 v176, 16, v232
	v_and_b32_e32 v232, 0xffff0000, v232
	v_lshlrev_b32_e32 v177, 16, v233
	v_and_b32_e32 v233, 0xffff0000, v233
	v_add_f32_e32 v30, v30, v156
	v_add_f32_e32 v31, v31, v230
	v_add_f32_e32 v32, v32, v157
	v_add_f32_e32 v33, v33, v231
	v_add_f32_e32 v26, v26, v176
	v_add_f32_e32 v27, v27, v232
	v_add_f32_e32 v28, v28, v177
	v_add_f32_e32 v29, v29, v233
	v_cvt_pk_bf16_f32 v230, v30, v31
	v_cvt_pk_bf16_f32 v231, v32, v33
	v_cvt_pk_bf16_f32 v232, v26, v27
	v_cvt_pk_bf16_f32 v233, v28, v29
	global_store_dwordx4 v141, v[230:233], s[56:57]
	v_mul_f32_e32 v156, v31, v31
	v_mul_f32_e32 v157, v33, v33
	v_fmac_f32_e32 v156, v30, v30
	v_fmac_f32_e32 v157, v32, v32
	v_add_f32_e32 v156, v156, v157
	v_mul_f32_e32 v176, v27, v27
	v_mul_f32_e32 v177, v29, v29
	v_fmac_f32_e32 v176, v26, v26
	v_fmac_f32_e32 v177, v28, v28
	v_add_f32_e32 v176, v176, v177
	v_add_f32_e32 v30, v156, v176
	s_waitcnt vmcnt(15)
	v_lshlrev_b32_e32 v156, 16, v234
	v_and_b32_e32 v234, 0xffff0000, v234
	v_lshlrev_b32_e32 v157, 16, v235
	v_and_b32_e32 v235, 0xffff0000, v235
	v_lshlrev_b32_e32 v176, 16, v236
	v_and_b32_e32 v236, 0xffff0000, v236
	v_lshlrev_b32_e32 v177, 16, v237
	v_and_b32_e32 v237, 0xffff0000, v237
	v_add_f32_e32 v22, v22, v156
	v_add_f32_e32 v23, v23, v234
	v_add_f32_e32 v24, v24, v157
	v_add_f32_e32 v25, v25, v235
	v_add_f32_e32 v18, v18, v176
	v_add_f32_e32 v19, v19, v236
	v_add_f32_e32 v20, v20, v177
	v_add_f32_e32 v21, v21, v237
	v_cvt_pk_bf16_f32 v234, v22, v23
	v_cvt_pk_bf16_f32 v235, v24, v25
	v_cvt_pk_bf16_f32 v236, v18, v19
	v_cvt_pk_bf16_f32 v237, v20, v21
	global_store_dwordx4 v141, v[234:237], s[56:57] offset:256
	v_mul_f32_e32 v156, v23, v23
	v_mul_f32_e32 v157, v25, v25
	v_fmac_f32_e32 v156, v22, v22
	v_fmac_f32_e32 v157, v24, v24
	v_add_f32_e32 v156, v156, v157
	v_mul_f32_e32 v176, v19, v19
	v_mul_f32_e32 v177, v21, v21
	v_fmac_f32_e32 v176, v18, v18
	v_fmac_f32_e32 v177, v20, v20
	v_add_f32_e32 v176, v176, v177
	v_add_f32_e32 v156, v156, v176
	v_add_f32_e32 v30, v30, v156
	s_add_u32 s56, s22, 0xb0000
	s_addc_u32 s57, s23, 0
	s_waitcnt vmcnt(15)
	v_lshlrev_b32_e32 v156, 16, v238
	v_and_b32_e32 v238, 0xffff0000, v238
	v_lshlrev_b32_e32 v157, 16, v239
	v_and_b32_e32 v239, 0xffff0000, v239
	v_lshlrev_b32_e32 v176, 16, v240
	v_and_b32_e32 v240, 0xffff0000, v240
	v_lshlrev_b32_e32 v177, 16, v241
	v_and_b32_e32 v241, 0xffff0000, v241
	v_add_f32_e32 v14, v14, v156
	v_add_f32_e32 v15, v15, v238
	v_add_f32_e32 v16, v16, v157
	v_add_f32_e32 v17, v17, v239
	v_add_f32_e32 v10, v10, v176
	v_add_f32_e32 v11, v11, v240
	v_add_f32_e32 v12, v12, v177
	v_add_f32_e32 v13, v13, v241
	v_cvt_pk_bf16_f32 v238, v14, v15
	v_cvt_pk_bf16_f32 v239, v16, v17
	v_cvt_pk_bf16_f32 v240, v10, v11
	v_cvt_pk_bf16_f32 v241, v12, v13
	global_store_dwordx4 v141, v[238:241], s[56:57]
	v_mul_f32_e32 v156, v15, v15
	v_mul_f32_e32 v157, v17, v17
	v_fmac_f32_e32 v156, v14, v14
	v_fmac_f32_e32 v157, v16, v16
	v_add_f32_e32 v156, v156, v157
	v_mul_f32_e32 v176, v11, v11
	v_mul_f32_e32 v177, v13, v13
	v_fmac_f32_e32 v176, v10, v10
	v_fmac_f32_e32 v177, v12, v12
	v_add_f32_e32 v176, v176, v177
	v_add_f32_e32 v14, v156, v176
	s_waitcnt vmcnt(15)
	v_lshlrev_b32_e32 v156, 16, v242
	v_and_b32_e32 v242, 0xffff0000, v242
	v_lshlrev_b32_e32 v157, 16, v243
	v_and_b32_e32 v243, 0xffff0000, v243
	v_lshlrev_b32_e32 v176, 16, v244
	v_and_b32_e32 v244, 0xffff0000, v244
	v_lshlrev_b32_e32 v177, 16, v245
	v_and_b32_e32 v245, 0xffff0000, v245
	v_add_f32_e32 v6, v6, v156
	v_add_f32_e32 v7, v7, v242
	v_add_f32_e32 v8, v8, v157
	v_add_f32_e32 v9, v9, v243
	v_add_f32_e32 v2, v2, v176
	v_add_f32_e32 v3, v3, v244
	v_add_f32_e32 v4, v4, v177
	v_add_f32_e32 v5, v5, v245
	v_cvt_pk_bf16_f32 v242, v6, v7
	v_cvt_pk_bf16_f32 v243, v8, v9
	v_cvt_pk_bf16_f32 v244, v2, v3
	v_cvt_pk_bf16_f32 v245, v4, v5
	global_store_dwordx4 v141, v[242:245], s[56:57] offset:256
	v_mul_f32_e32 v156, v7, v7
	v_mul_f32_e32 v157, v9, v9
	v_fmac_f32_e32 v156, v6, v6
	v_fmac_f32_e32 v157, v8, v8
	v_add_f32_e32 v156, v156, v157
	v_mul_f32_e32 v176, v3, v3
	v_mul_f32_e32 v177, v5, v5
	v_fmac_f32_e32 v176, v2, v2
	v_fmac_f32_e32 v177, v4, v4
	v_add_f32_e32 v176, v176, v177
	v_add_f32_e32 v156, v156, v176
	v_add_f32_e32 v14, v14, v156
	ds_bpermute_b32 v114, v178, v126
	ds_bpermute_b32 v98, v178, v110
	ds_bpermute_b32 v82, v178, v94
	ds_bpermute_b32 v66, v178, v78
	ds_bpermute_b32 v50, v178, v62
	ds_bpermute_b32 v34, v178, v46
	ds_bpermute_b32 v18, v178, v30
	ds_bpermute_b32 v2, v178, v14
	s_waitcnt lgkmcnt(7)
	v_add_f32_e32 v126, v126, v114
	s_waitcnt lgkmcnt(6)
	v_add_f32_e32 v110, v110, v98
	s_waitcnt lgkmcnt(5)
	v_add_f32_e32 v94, v94, v82
	s_waitcnt lgkmcnt(4)
	v_add_f32_e32 v78, v78, v66
	s_waitcnt lgkmcnt(3)
	v_add_f32_e32 v62, v62, v50
	s_waitcnt lgkmcnt(2)
	v_add_f32_e32 v46, v46, v34
	s_waitcnt lgkmcnt(1)
	v_add_f32_e32 v30, v30, v18
	s_waitcnt lgkmcnt(0)
	v_add_f32_e32 v14, v14, v2
	ds_bpermute_b32 v114, v208, v126
	ds_bpermute_b32 v98, v208, v110
	ds_bpermute_b32 v82, v208, v94
	ds_bpermute_b32 v66, v208, v78
	ds_bpermute_b32 v50, v208, v62
	ds_bpermute_b32 v34, v208, v46
	ds_bpermute_b32 v18, v208, v30
	ds_bpermute_b32 v2, v208, v14
	s_lshl_b32 s2, s9, 4
	s_lshl_b32 s12, s75, 2
	s_add_i32 s2, s2, s12
	s_add_u32 s56, s24, s2
	s_addc_u32 s57, s25, 0
	s_waitcnt lgkmcnt(7)
	v_add_f32_e32 v126, v126, v114
	s_waitcnt lgkmcnt(6)
	v_add_f32_e32 v110, v110, v98
	s_waitcnt lgkmcnt(5)
	v_add_f32_e32 v94, v94, v82
	s_waitcnt lgkmcnt(4)
	v_add_f32_e32 v78, v78, v66
	s_waitcnt lgkmcnt(3)
	v_add_f32_e32 v62, v62, v50
	s_waitcnt lgkmcnt(2)
	v_add_f32_e32 v46, v46, v34
	s_waitcnt lgkmcnt(1)
	v_add_f32_e32 v30, v30, v18
	s_waitcnt lgkmcnt(0)
	v_add_f32_e32 v14, v14, v2
	s_and_saveexec_b64 vcc, s[38:39]
	global_store_dword v209, v126, s[56:57]
	global_store_dword v209, v110, s[56:57] offset:2048
	s_add_u32 s2, s56, 0x1000
	s_addc_u32 s3, s57, 0
	global_store_dword v209, v94, s[2:3]
	s_add_u32 s2, s56, 0x1800
	s_addc_u32 s3, s57, 0
	global_store_dword v209, v78, s[2:3]
	s_add_u32 s2, s56, 0x4000
	s_addc_u32 s3, s57, 0
	global_store_dword v209, v62, s[2:3]
	s_add_u32 s2, s56, 0x4800
	s_addc_u32 s3, s57, 0
	global_store_dword v209, v46, s[2:3]
	s_add_u32 s2, s56, 0x5000
	s_addc_u32 s3, s57, 0
	global_store_dword v209, v30, s[2:3]
	s_add_u32 s2, s56, 0x5800
	s_addc_u32 s3, s57, 0
	global_store_dword v209, v14, s[2:3]
	s_mov_b64 exec, vcc
	s_mov_b64 s[56:57], exec

.LBB0_1814:
	v_lshlrev_b32_e32 v144, 12, v142
	v_lshl_add_u32 v144, v140, 1, v144
	global_load_dwordx4 v[150:153], v144, s[22:23]
	global_load_dwordx4 v[154:157], v144, s[22:23] offset:256
	s_add_u32 s52, s22, 0x10000
	s_addc_u32 s53, s23, 0
	global_load_dwordx4 v[168:171], v144, s[52:53]
	global_load_dwordx4 v[172:175], v144, s[52:53] offset:256
	s_add_u32 s52, s22, 0x20000
	s_addc_u32 s53, s23, 0
	global_load_dwordx4 v[180:183], v144, s[52:53]
	global_load_dwordx4 v[184:187], v144, s[52:53] offset:256
	s_add_u32 s52, s22, 0x30000
	s_addc_u32 s53, s23, 0
	global_load_dwordx4 v[188:191], v144, s[52:53]
	global_load_dwordx4 v[192:195], v144, s[52:53] offset:256
	s_add_u32 s52, s22, 0x80000
	s_addc_u32 s53, s23, 0
	global_load_dwordx4 v[196:199], v144, s[52:53]
	global_load_dwordx4 v[200:203], v144, s[52:53] offset:256
	s_add_u32 s52, s22, 0x90000
	s_addc_u32 s53, s23, 0
	global_load_dwordx4 v[204:207], v144, s[52:53]
	global_load_dwordx4 v[214:217], v144, s[52:53] offset:256
	s_add_u32 s52, s22, 0xa0000
	s_addc_u32 s53, s23, 0
	global_load_dwordx4 v[230:233], v144, s[52:53]
	global_load_dwordx4 v[234:237], v144, s[52:53] offset:256
	s_add_u32 s52, s22, 0xb0000
	s_addc_u32 s53, s23, 0
	global_load_dwordx4 v[238:241], v144, s[52:53]
	global_load_dwordx4 v[242:245], v144, s[52:53] offset:256
	v_xor_b32_e32 v208, 16, v1
	v_xor_b32_e32 v209, 32, v1
	v_lshlrev_b32_e32 v208, 2, v208
	v_lshlrev_b32_e32 v209, 2, v209
	v_lshlrev_b32_e32 v218, 7, v142
	s_waitcnt vmcnt(15)
	v_lshlrev_b32_e32 v145, 16, v150
	v_and_b32_e32 v150, 0xffff0000, v150
	v_lshlrev_b32_e32 v176, 16, v151
	v_and_b32_e32 v151, 0xffff0000, v151
	v_lshlrev_b32_e32 v177, 16, v152
	v_and_b32_e32 v152, 0xffff0000, v152
	v_lshlrev_b32_e32 v178, 16, v153
	v_and_b32_e32 v153, 0xffff0000, v153
	v_add_f32_e32 v126, v126, v145
	v_add_f32_e32 v127, v127, v150
	v_add_f32_e32 v128, v128, v176
	v_add_f32_e32 v129, v129, v151
	v_add_f32_e32 v122, v122, v177
	v_add_f32_e32 v123, v123, v152
	v_add_f32_e32 v124, v124, v178
	v_add_f32_e32 v125, v125, v153
	v_cvt_pk_bf16_f32 v150, v126, v127
	v_cvt_pk_bf16_f32 v151, v128, v129
	v_cvt_pk_bf16_f32 v152, v122, v123
	v_cvt_pk_bf16_f32 v153, v124, v125
	global_store_dwordx4 v144, v[150:153], s[22:23]
	v_mul_f32_e32 v145, v127, v127
	v_mul_f32_e32 v176, v129, v129
	v_fmac_f32_e32 v145, v126, v126
	v_fmac_f32_e32 v176, v128, v128
	v_add_f32_e32 v145, v145, v176
	v_mul_f32_e32 v177, v123, v123
	v_mul_f32_e32 v178, v125, v125
	v_fmac_f32_e32 v177, v122, v122
	v_fmac_f32_e32 v178, v124, v124
	v_add_f32_e32 v177, v177, v178
	v_add_f32_e32 v126, v145, v177
	s_waitcnt vmcnt(15)
	v_lshlrev_b32_e32 v145, 16, v154
	v_and_b32_e32 v154, 0xffff0000, v154
	v_lshlrev_b32_e32 v176, 16, v155
	v_and_b32_e32 v155, 0xffff0000, v155
	v_lshlrev_b32_e32 v177, 16, v156
	v_and_b32_e32 v156, 0xffff0000, v156
	v_lshlrev_b32_e32 v178, 16, v157
	v_and_b32_e32 v157, 0xffff0000, v157
	v_add_f32_e32 v118, v118, v145
	v_add_f32_e32 v119, v119, v154
	v_add_f32_e32 v120, v120, v176
	v_add_f32_e32 v121, v121, v155
	v_add_f32_e32 v114, v114, v177
	v_add_f32_e32 v115, v115, v156
	v_add_f32_e32 v116, v116, v178
	v_add_f32_e32 v117, v117, v157
	v_cvt_pk_bf16_f32 v154, v118, v119
	v_cvt_pk_bf16_f32 v155, v120, v121
	v_cvt_pk_bf16_f32 v156, v114, v115
	v_cvt_pk_bf16_f32 v157, v116, v117
	global_store_dwordx4 v144, v[154:157], s[22:23] offset:256
	v_mul_f32_e32 v145, v119, v119
	v_mul_f32_e32 v176, v121, v121
	v_fmac_f32_e32 v145, v118, v118
	v_fmac_f32_e32 v176, v120, v120
	v_add_f32_e32 v145, v145, v176
	v_mul_f32_e32 v177, v115, v115
	v_mul_f32_e32 v178, v117, v117
	v_fmac_f32_e32 v177, v114, v114
	v_fmac_f32_e32 v178, v116, v116
	v_add_f32_e32 v177, v177, v178
	v_add_f32_e32 v145, v145, v177
	v_add_f32_e32 v126, v126, v145
	s_add_u32 s52, s22, 0x10000
	s_addc_u32 s53, s23, 0
	s_waitcnt vmcnt(15)
	v_lshlrev_b32_e32 v145, 16, v168
	v_and_b32_e32 v168, 0xffff0000, v168
	v_lshlrev_b32_e32 v176, 16, v169
	v_and_b32_e32 v169, 0xffff0000, v169
	v_lshlrev_b32_e32 v177, 16, v170
	v_and_b32_e32 v170, 0xffff0000, v170
	v_lshlrev_b32_e32 v178, 16, v171
	v_and_b32_e32 v171, 0xffff0000, v171
	v_add_f32_e32 v110, v110, v145
	v_add_f32_e32 v111, v111, v168
	v_add_f32_e32 v112, v112, v176
	v_add_f32_e32 v113, v113, v169
	v_add_f32_e32 v106, v106, v177
	v_add_f32_e32 v107, v107, v170
	v_add_f32_e32 v108, v108, v178
	v_add_f32_e32 v109, v109, v171
	v_cvt_pk_bf16_f32 v168, v110, v111
	v_cvt_pk_bf16_f32 v169, v112, v113
	v_cvt_pk_bf16_f32 v170, v106, v107
	v_cvt_pk_bf16_f32 v171, v108, v109
	global_store_dwordx4 v144, v[168:171], s[52:53]
	v_mul_f32_e32 v145, v111, v111
	v_mul_f32_e32 v176, v113, v113
	v_fmac_f32_e32 v145, v110, v110
	v_fmac_f32_e32 v176, v112, v112
	v_add_f32_e32 v145, v145, v176
	v_mul_f32_e32 v177, v107, v107
	v_mul_f32_e32 v178, v109, v109
	v_fmac_f32_e32 v177, v106, v106
	v_fmac_f32_e32 v178, v108, v108
	v_add_f32_e32 v177, v177, v178
	v_add_f32_e32 v110, v145, v177
	s_waitcnt vmcnt(15)
	v_lshlrev_b32_e32 v145, 16, v172
	v_and_b32_e32 v172, 0xffff0000, v172
	v_lshlrev_b32_e32 v176, 16, v173
	v_and_b32_e32 v173, 0xffff0000, v173
	v_lshlrev_b32_e32 v177, 16, v174
	v_and_b32_e32 v174, 0xffff0000, v174
	v_lshlrev_b32_e32 v178, 16, v175
	v_and_b32_e32 v175, 0xffff0000, v175
	v_add_f32_e32 v102, v102, v145
	v_add_f32_e32 v103, v103, v172
	v_add_f32_e32 v104, v104, v176
	v_add_f32_e32 v105, v105, v173
	v_add_f32_e32 v98, v98, v177
	v_add_f32_e32 v99, v99, v174
	v_add_f32_e32 v100, v100, v178
	v_add_f32_e32 v101, v101, v175
	v_cvt_pk_bf16_f32 v172, v102, v103
	v_cvt_pk_bf16_f32 v173, v104, v105
	v_cvt_pk_bf16_f32 v174, v98, v99
	v_cvt_pk_bf16_f32 v175, v100, v101
	global_store_dwordx4 v144, v[172:175], s[52:53] offset:256
	v_mul_f32_e32 v145, v103, v103
	v_mul_f32_e32 v176, v105, v105
	v_fmac_f32_e32 v145, v102, v102
	v_fmac_f32_e32 v176, v104, v104
	v_add_f32_e32 v145, v145, v176
	v_mul_f32_e32 v177, v99, v99
	v_mul_f32_e32 v178, v101, v101
	v_fmac_f32_e32 v177, v98, v98
	v_fmac_f32_e32 v178, v100, v100
	v_add_f32_e32 v177, v177, v178
	v_add_f32_e32 v145, v145, v177
	v_add_f32_e32 v110, v110, v145
	s_add_u32 s52, s22, 0x20000
	s_addc_u32 s53, s23, 0
	s_waitcnt vmcnt(15)
	v_lshlrev_b32_e32 v145, 16, v180
	v_and_b32_e32 v180, 0xffff0000, v180
	v_lshlrev_b32_e32 v176, 16, v181
	v_and_b32_e32 v181, 0xffff0000, v181
	v_lshlrev_b32_e32 v177, 16, v182
	v_and_b32_e32 v182, 0xffff0000, v182
	v_lshlrev_b32_e32 v178, 16, v183
	v_and_b32_e32 v183, 0xffff0000, v183
	v_add_f32_e32 v94, v94, v145
	v_add_f32_e32 v95, v95, v180
	v_add_f32_e32 v96, v96, v176
	v_add_f32_e32 v97, v97, v181
	v_add_f32_e32 v90, v90, v177
	v_add_f32_e32 v91, v91, v182
	v_add_f32_e32 v92, v92, v178
	v_add_f32_e32 v93, v93, v183
	v_cvt_pk_bf16_f32 v180, v94, v95
	v_cvt_pk_bf16_f32 v181, v96, v97
	v_cvt_pk_bf16_f32 v182, v90, v91
	v_cvt_pk_bf16_f32 v183, v92, v93
	global_store_dwordx4 v144, v[180:183], s[52:53]
	v_mul_f32_e32 v145, v95, v95
	v_mul_f32_e32 v176, v97, v97
	v_fmac_f32_e32 v145, v94, v94
	v_fmac_f32_e32 v176, v96, v96
	v_add_f32_e32 v145, v145, v176
	v_mul_f32_e32 v177, v91, v91
	v_mul_f32_e32 v178, v93, v93
	v_fmac_f32_e32 v177, v90, v90
	v_fmac_f32_e32 v178, v92, v92
	v_add_f32_e32 v177, v177, v178
	v_add_f32_e32 v94, v145, v177
	s_waitcnt vmcnt(15)
	v_lshlrev_b32_e32 v145, 16, v184
	v_and_b32_e32 v184, 0xffff0000, v184
	v_lshlrev_b32_e32 v176, 16, v185
	v_and_b32_e32 v185, 0xffff0000, v185
	v_lshlrev_b32_e32 v177, 16, v186
	v_and_b32_e32 v186, 0xffff0000, v186
	v_lshlrev_b32_e32 v178, 16, v187
	v_and_b32_e32 v187, 0xffff0000, v187
	v_add_f32_e32 v86, v86, v145
	v_add_f32_e32 v87, v87, v184
	v_add_f32_e32 v88, v88, v176
	v_add_f32_e32 v89, v89, v185
	v_add_f32_e32 v82, v82, v177
	v_add_f32_e32 v83, v83, v186
	v_add_f32_e32 v84, v84, v178
	v_add_f32_e32 v85, v85, v187
	v_cvt_pk_bf16_f32 v184, v86, v87
	v_cvt_pk_bf16_f32 v185, v88, v89
	v_cvt_pk_bf16_f32 v186, v82, v83
	v_cvt_pk_bf16_f32 v187, v84, v85
	global_store_dwordx4 v144, v[184:187], s[52:53] offset:256
	v_mul_f32_e32 v145, v87, v87
	v_mul_f32_e32 v176, v89, v89
	v_fmac_f32_e32 v145, v86, v86
	v_fmac_f32_e32 v176, v88, v88
	v_add_f32_e32 v145, v145, v176
	v_mul_f32_e32 v177, v83, v83
	v_mul_f32_e32 v178, v85, v85
	v_fmac_f32_e32 v177, v82, v82
	v_fmac_f32_e32 v178, v84, v84
	v_add_f32_e32 v177, v177, v178
	v_add_f32_e32 v145, v145, v177
	v_add_f32_e32 v94, v94, v145
	s_add_u32 s52, s22, 0x30000
	s_addc_u32 s53, s23, 0
	s_waitcnt vmcnt(15)
	v_lshlrev_b32_e32 v145, 16, v188
	v_and_b32_e32 v188, 0xffff0000, v188
	v_lshlrev_b32_e32 v176, 16, v189
	v_and_b32_e32 v189, 0xffff0000, v189
	v_lshlrev_b32_e32 v177, 16, v190
	v_and_b32_e32 v190, 0xffff0000, v190
	v_lshlrev_b32_e32 v178, 16, v191
	v_and_b32_e32 v191, 0xffff0000, v191
	v_add_f32_e32 v78, v78, v145
	v_add_f32_e32 v79, v79, v188
	v_add_f32_e32 v80, v80, v176
	v_add_f32_e32 v81, v81, v189
	v_add_f32_e32 v74, v74, v177
	v_add_f32_e32 v75, v75, v190
	v_add_f32_e32 v76, v76, v178
	v_add_f32_e32 v77, v77, v191
	v_cvt_pk_bf16_f32 v188, v78, v79
	v_cvt_pk_bf16_f32 v189, v80, v81
	v_cvt_pk_bf16_f32 v190, v74, v75
	v_cvt_pk_bf16_f32 v191, v76, v77
	global_store_dwordx4 v144, v[188:191], s[52:53]
	v_mul_f32_e32 v145, v79, v79
	v_mul_f32_e32 v176, v81, v81
	v_fmac_f32_e32 v145, v78, v78
	v_fmac_f32_e32 v176, v80, v80
	v_add_f32_e32 v145, v145, v176
	v_mul_f32_e32 v177, v75, v75
	v_mul_f32_e32 v178, v77, v77
	v_fmac_f32_e32 v177, v74, v74
	v_fmac_f32_e32 v178, v76, v76
	v_add_f32_e32 v177, v177, v178
	v_add_f32_e32 v78, v145, v177
	s_waitcnt vmcnt(15)
	v_lshlrev_b32_e32 v145, 16, v192
	v_and_b32_e32 v192, 0xffff0000, v192
	v_lshlrev_b32_e32 v176, 16, v193
	v_and_b32_e32 v193, 0xffff0000, v193
	v_lshlrev_b32_e32 v177, 16, v194
	v_and_b32_e32 v194, 0xffff0000, v194
	v_lshlrev_b32_e32 v178, 16, v195
	v_and_b32_e32 v195, 0xffff0000, v195
	v_add_f32_e32 v70, v70, v145
	v_add_f32_e32 v71, v71, v192
	v_add_f32_e32 v72, v72, v176
	v_add_f32_e32 v73, v73, v193
	v_add_f32_e32 v66, v66, v177
	v_add_f32_e32 v67, v67, v194
	v_add_f32_e32 v68, v68, v178
	v_add_f32_e32 v69, v69, v195
	v_cvt_pk_bf16_f32 v192, v70, v71
	v_cvt_pk_bf16_f32 v193, v72, v73
	v_cvt_pk_bf16_f32 v194, v66, v67
	v_cvt_pk_bf16_f32 v195, v68, v69
	global_store_dwordx4 v144, v[192:195], s[52:53] offset:256
	v_mul_f32_e32 v145, v71, v71
	v_mul_f32_e32 v176, v73, v73
	v_fmac_f32_e32 v145, v70, v70
	v_fmac_f32_e32 v176, v72, v72
	v_add_f32_e32 v145, v145, v176
	v_mul_f32_e32 v177, v67, v67
	v_mul_f32_e32 v178, v69, v69
	v_fmac_f32_e32 v177, v66, v66
	v_fmac_f32_e32 v178, v68, v68
	v_add_f32_e32 v177, v177, v178
	v_add_f32_e32 v145, v145, v177
	v_add_f32_e32 v78, v78, v145
	s_add_u32 s52, s22, 0x80000
	s_addc_u32 s53, s23, 0
	s_waitcnt vmcnt(15)
	v_lshlrev_b32_e32 v145, 16, v196
	v_and_b32_e32 v196, 0xffff0000, v196
	v_lshlrev_b32_e32 v176, 16, v197
	v_and_b32_e32 v197, 0xffff0000, v197
	v_lshlrev_b32_e32 v177, 16, v198
	v_and_b32_e32 v198, 0xffff0000, v198
	v_lshlrev_b32_e32 v178, 16, v199
	v_and_b32_e32 v199, 0xffff0000, v199
	v_add_f32_e32 v62, v62, v145
	v_add_f32_e32 v63, v63, v196
	v_add_f32_e32 v64, v64, v176
	v_add_f32_e32 v65, v65, v197
	v_add_f32_e32 v58, v58, v177
	v_add_f32_e32 v59, v59, v198
	v_add_f32_e32 v60, v60, v178
	v_add_f32_e32 v61, v61, v199
	v_cvt_pk_bf16_f32 v196, v62, v63
	v_cvt_pk_bf16_f32 v197, v64, v65
	v_cvt_pk_bf16_f32 v198, v58, v59
	v_cvt_pk_bf16_f32 v199, v60, v61
	global_store_dwordx4 v144, v[196:199], s[52:53]
	v_mul_f32_e32 v145, v63, v63
	v_mul_f32_e32 v176, v65, v65
	v_fmac_f32_e32 v145, v62, v62
	v_fmac_f32_e32 v176, v64, v64
	v_add_f32_e32 v145, v145, v176
	v_mul_f32_e32 v177, v59, v59
	v_mul_f32_e32 v178, v61, v61
	v_fmac_f32_e32 v177, v58, v58
	v_fmac_f32_e32 v178, v60, v60
	v_add_f32_e32 v177, v177, v178
	v_add_f32_e32 v62, v145, v177
	s_waitcnt vmcnt(15)
	v_lshlrev_b32_e32 v145, 16, v200
	v_and_b32_e32 v200, 0xffff0000, v200
	v_lshlrev_b32_e32 v176, 16, v201
	v_and_b32_e32 v201, 0xffff0000, v201
	v_lshlrev_b32_e32 v177, 16, v202
	v_and_b32_e32 v202, 0xffff0000, v202
	v_lshlrev_b32_e32 v178, 16, v203
	v_and_b32_e32 v203, 0xffff0000, v203
	v_add_f32_e32 v54, v54, v145
	v_add_f32_e32 v55, v55, v200
	v_add_f32_e32 v56, v56, v176
	v_add_f32_e32 v57, v57, v201
	v_add_f32_e32 v50, v50, v177
	v_add_f32_e32 v51, v51, v202
	v_add_f32_e32 v52, v52, v178
	v_add_f32_e32 v53, v53, v203
	v_cvt_pk_bf16_f32 v200, v54, v55
	v_cvt_pk_bf16_f32 v201, v56, v57
	v_cvt_pk_bf16_f32 v202, v50, v51
	v_cvt_pk_bf16_f32 v203, v52, v53
	global_store_dwordx4 v144, v[200:203], s[52:53] offset:256
	v_mul_f32_e32 v145, v55, v55
	v_mul_f32_e32 v176, v57, v57
	v_fmac_f32_e32 v145, v54, v54
	v_fmac_f32_e32 v176, v56, v56
	v_add_f32_e32 v145, v145, v176
	v_mul_f32_e32 v177, v51, v51
	v_mul_f32_e32 v178, v53, v53
	v_fmac_f32_e32 v177, v50, v50
	v_fmac_f32_e32 v178, v52, v52
	v_add_f32_e32 v177, v177, v178
	v_add_f32_e32 v145, v145, v177
	v_add_f32_e32 v62, v62, v145
	s_add_u32 s52, s22, 0x90000
	s_addc_u32 s53, s23, 0
	s_waitcnt vmcnt(15)
	v_lshlrev_b32_e32 v145, 16, v204
	v_and_b32_e32 v204, 0xffff0000, v204
	v_lshlrev_b32_e32 v176, 16, v205
	v_and_b32_e32 v205, 0xffff0000, v205
	v_lshlrev_b32_e32 v177, 16, v206
	v_and_b32_e32 v206, 0xffff0000, v206
	v_lshlrev_b32_e32 v178, 16, v207
	v_and_b32_e32 v207, 0xffff0000, v207
	v_add_f32_e32 v46, v46, v145
	v_add_f32_e32 v47, v47, v204
	v_add_f32_e32 v48, v48, v176
	v_add_f32_e32 v49, v49, v205
	v_add_f32_e32 v42, v42, v177
	v_add_f32_e32 v43, v43, v206
	v_add_f32_e32 v44, v44, v178
	v_add_f32_e32 v45, v45, v207
	v_cvt_pk_bf16_f32 v204, v46, v47
	v_cvt_pk_bf16_f32 v205, v48, v49
	v_cvt_pk_bf16_f32 v206, v42, v43
	v_cvt_pk_bf16_f32 v207, v44, v45
	global_store_dwordx4 v144, v[204:207], s[52:53]
	v_mul_f32_e32 v145, v47, v47
	v_mul_f32_e32 v176, v49, v49
	v_fmac_f32_e32 v145, v46, v46
	v_fmac_f32_e32 v176, v48, v48
	v_add_f32_e32 v145, v145, v176
	v_mul_f32_e32 v177, v43, v43
	v_mul_f32_e32 v178, v45, v45
	v_fmac_f32_e32 v177, v42, v42
	v_fmac_f32_e32 v178, v44, v44
	v_add_f32_e32 v177, v177, v178
	v_add_f32_e32 v46, v145, v177
	s_waitcnt vmcnt(15)
	v_lshlrev_b32_e32 v145, 16, v214
	v_and_b32_e32 v214, 0xffff0000, v214
	v_lshlrev_b32_e32 v176, 16, v215
	v_and_b32_e32 v215, 0xffff0000, v215
	v_lshlrev_b32_e32 v177, 16, v216
	v_and_b32_e32 v216, 0xffff0000, v216
	v_lshlrev_b32_e32 v178, 16, v217
	v_and_b32_e32 v217, 0xffff0000, v217
	v_add_f32_e32 v38, v38, v145
	v_add_f32_e32 v39, v39, v214
	v_add_f32_e32 v40, v40, v176
	v_add_f32_e32 v41, v41, v215
	v_add_f32_e32 v34, v34, v177
	v_add_f32_e32 v35, v35, v216
	v_add_f32_e32 v36, v36, v178
	v_add_f32_e32 v37, v37, v217
	v_cvt_pk_bf16_f32 v214, v38, v39
	v_cvt_pk_bf16_f32 v215, v40, v41
	v_cvt_pk_bf16_f32 v216, v34, v35
	v_cvt_pk_bf16_f32 v217, v36, v37
	global_store_dwordx4 v144, v[214:217], s[52:53] offset:256
	v_mul_f32_e32 v145, v39, v39
	v_mul_f32_e32 v176, v41, v41
	v_fmac_f32_e32 v145, v38, v38
	v_fmac_f32_e32 v176, v40, v40
	v_add_f32_e32 v145, v145, v176
	v_mul_f32_e32 v177, v35, v35
	v_mul_f32_e32 v178, v37, v37
	v_fmac_f32_e32 v177, v34, v34
	v_fmac_f32_e32 v178, v36, v36
	v_add_f32_e32 v177, v177, v178
	v_add_f32_e32 v145, v145, v177
	v_add_f32_e32 v46, v46, v145
	s_add_u32 s52, s22, 0xa0000
	s_addc_u32 s53, s23, 0
	s_waitcnt vmcnt(15)
	v_lshlrev_b32_e32 v145, 16, v230
	v_and_b32_e32 v230, 0xffff0000, v230
	v_lshlrev_b32_e32 v176, 16, v231
	v_and_b32_e32 v231, 0xffff0000, v231
	v_lshlrev_b32_e32 v177, 16, v232
	v_and_b32_e32 v232, 0xffff0000, v232
	v_lshlrev_b32_e32 v178, 16, v233
	v_and_b32_e32 v233, 0xffff0000, v233
	v_add_f32_e32 v30, v30, v145
	v_add_f32_e32 v31, v31, v230
	v_add_f32_e32 v32, v32, v176
	v_add_f32_e32 v33, v33, v231
	v_add_f32_e32 v26, v26, v177
	v_add_f32_e32 v27, v27, v232
	v_add_f32_e32 v28, v28, v178
	v_add_f32_e32 v29, v29, v233
	v_cvt_pk_bf16_f32 v230, v30, v31
	v_cvt_pk_bf16_f32 v231, v32, v33
	v_cvt_pk_bf16_f32 v232, v26, v27
	v_cvt_pk_bf16_f32 v233, v28, v29
	global_store_dwordx4 v144, v[230:233], s[52:53]
	v_mul_f32_e32 v145, v31, v31
	v_mul_f32_e32 v176, v33, v33
	v_fmac_f32_e32 v145, v30, v30
	v_fmac_f32_e32 v176, v32, v32
	v_add_f32_e32 v145, v145, v176
	v_mul_f32_e32 v177, v27, v27
	v_mul_f32_e32 v178, v29, v29
	v_fmac_f32_e32 v177, v26, v26
	v_fmac_f32_e32 v178, v28, v28
	v_add_f32_e32 v177, v177, v178
	v_add_f32_e32 v30, v145, v177
	s_waitcnt vmcnt(15)
	v_lshlrev_b32_e32 v145, 16, v234
	v_and_b32_e32 v234, 0xffff0000, v234
	v_lshlrev_b32_e32 v176, 16, v235
	v_and_b32_e32 v235, 0xffff0000, v235
	v_lshlrev_b32_e32 v177, 16, v236
	v_and_b32_e32 v236, 0xffff0000, v236
	v_lshlrev_b32_e32 v178, 16, v237
	v_and_b32_e32 v237, 0xffff0000, v237
	v_add_f32_e32 v22, v22, v145
	v_add_f32_e32 v23, v23, v234
	v_add_f32_e32 v24, v24, v176
	v_add_f32_e32 v25, v25, v235
	v_add_f32_e32 v18, v18, v177
	v_add_f32_e32 v19, v19, v236
	v_add_f32_e32 v20, v20, v178
	v_add_f32_e32 v21, v21, v237
	v_cvt_pk_bf16_f32 v234, v22, v23
	v_cvt_pk_bf16_f32 v235, v24, v25
	v_cvt_pk_bf16_f32 v236, v18, v19
	v_cvt_pk_bf16_f32 v237, v20, v21
	global_store_dwordx4 v144, v[234:237], s[52:53] offset:256
	v_mul_f32_e32 v145, v23, v23
	v_mul_f32_e32 v176, v25, v25
	v_fmac_f32_e32 v145, v22, v22
	v_fmac_f32_e32 v176, v24, v24
	v_add_f32_e32 v145, v145, v176
	v_mul_f32_e32 v177, v19, v19
	v_mul_f32_e32 v178, v21, v21
	v_fmac_f32_e32 v177, v18, v18
	v_fmac_f32_e32 v178, v20, v20
	v_add_f32_e32 v177, v177, v178
	v_add_f32_e32 v145, v145, v177
	v_add_f32_e32 v30, v30, v145
	s_add_u32 s52, s22, 0xb0000
	s_addc_u32 s53, s23, 0
	s_waitcnt vmcnt(15)
	v_lshlrev_b32_e32 v145, 16, v238
	v_and_b32_e32 v238, 0xffff0000, v238
	v_lshlrev_b32_e32 v176, 16, v239
	v_and_b32_e32 v239, 0xffff0000, v239
	v_lshlrev_b32_e32 v177, 16, v240
	v_and_b32_e32 v240, 0xffff0000, v240
	v_lshlrev_b32_e32 v178, 16, v241
	v_and_b32_e32 v241, 0xffff0000, v241
	v_add_f32_e32 v14, v14, v145
	v_add_f32_e32 v15, v15, v238
	v_add_f32_e32 v16, v16, v176
	v_add_f32_e32 v17, v17, v239
	v_add_f32_e32 v10, v10, v177
	v_add_f32_e32 v11, v11, v240
	v_add_f32_e32 v12, v12, v178
	v_add_f32_e32 v13, v13, v241
	v_cvt_pk_bf16_f32 v238, v14, v15
	v_cvt_pk_bf16_f32 v239, v16, v17
	v_cvt_pk_bf16_f32 v240, v10, v11
	v_cvt_pk_bf16_f32 v241, v12, v13
	global_store_dwordx4 v144, v[238:241], s[52:53]
	v_mul_f32_e32 v145, v15, v15
	v_mul_f32_e32 v176, v17, v17
	v_fmac_f32_e32 v145, v14, v14
	v_fmac_f32_e32 v176, v16, v16
	v_add_f32_e32 v145, v145, v176
	v_mul_f32_e32 v177, v11, v11
	v_mul_f32_e32 v178, v13, v13
	v_fmac_f32_e32 v177, v10, v10
	v_fmac_f32_e32 v178, v12, v12
	v_add_f32_e32 v177, v177, v178
	v_add_f32_e32 v14, v145, v177
	s_waitcnt vmcnt(15)
	v_lshlrev_b32_e32 v145, 16, v242
	v_and_b32_e32 v242, 0xffff0000, v242
	v_lshlrev_b32_e32 v176, 16, v243
	v_and_b32_e32 v243, 0xffff0000, v243
	v_lshlrev_b32_e32 v177, 16, v244
	v_and_b32_e32 v244, 0xffff0000, v244
	v_lshlrev_b32_e32 v178, 16, v245
	v_and_b32_e32 v245, 0xffff0000, v245
	v_add_f32_e32 v6, v6, v145
	v_add_f32_e32 v7, v7, v242
	v_add_f32_e32 v8, v8, v176
	v_add_f32_e32 v9, v9, v243
	v_add_f32_e32 v2, v2, v177
	v_add_f32_e32 v3, v3, v244
	v_add_f32_e32 v4, v4, v178
	v_add_f32_e32 v5, v5, v245
	v_cvt_pk_bf16_f32 v242, v6, v7
	v_cvt_pk_bf16_f32 v243, v8, v9
	v_cvt_pk_bf16_f32 v244, v2, v3
	v_cvt_pk_bf16_f32 v245, v4, v5
	global_store_dwordx4 v144, v[242:245], s[52:53] offset:256
	v_mul_f32_e32 v145, v7, v7
	v_mul_f32_e32 v176, v9, v9
	v_fmac_f32_e32 v145, v6, v6
	v_fmac_f32_e32 v176, v8, v8
	v_add_f32_e32 v145, v145, v176
	v_mul_f32_e32 v177, v3, v3
	v_mul_f32_e32 v178, v5, v5
	v_fmac_f32_e32 v177, v2, v2
	v_fmac_f32_e32 v178, v4, v4
	v_add_f32_e32 v177, v177, v178
	v_add_f32_e32 v145, v145, v177
	v_add_f32_e32 v14, v14, v145
	ds_bpermute_b32 v114, v208, v126
	ds_bpermute_b32 v98, v208, v110
	ds_bpermute_b32 v82, v208, v94
	ds_bpermute_b32 v66, v208, v78
	ds_bpermute_b32 v50, v208, v62
	ds_bpermute_b32 v34, v208, v46
	ds_bpermute_b32 v18, v208, v30
	ds_bpermute_b32 v2, v208, v14
	s_waitcnt lgkmcnt(7)
	v_add_f32_e32 v126, v126, v114
	s_waitcnt lgkmcnt(6)
	v_add_f32_e32 v110, v110, v98
	s_waitcnt lgkmcnt(5)
	v_add_f32_e32 v94, v94, v82
	s_waitcnt lgkmcnt(4)
	v_add_f32_e32 v78, v78, v66
	s_waitcnt lgkmcnt(3)
	v_add_f32_e32 v62, v62, v50
	s_waitcnt lgkmcnt(2)
	v_add_f32_e32 v46, v46, v34
	s_waitcnt lgkmcnt(1)
	v_add_f32_e32 v30, v30, v18
	s_waitcnt lgkmcnt(0)
	v_add_f32_e32 v14, v14, v2
	ds_bpermute_b32 v114, v209, v126
	ds_bpermute_b32 v98, v209, v110
	ds_bpermute_b32 v82, v209, v94
	ds_bpermute_b32 v66, v209, v78
	ds_bpermute_b32 v50, v209, v62
	ds_bpermute_b32 v34, v209, v46
	ds_bpermute_b32 v18, v209, v30
	ds_bpermute_b32 v2, v209, v14
	s_lshl_b32 s54, s8, 4
	s_lshl_b32 s12, s87, 2
	s_add_i32 s54, s54, s12
	s_add_u32 s52, s24, s54
	s_addc_u32 s53, s25, 0
	s_waitcnt lgkmcnt(7)
	v_add_f32_e32 v126, v126, v114
	s_waitcnt lgkmcnt(6)
	v_add_f32_e32 v110, v110, v98
	s_waitcnt lgkmcnt(5)
	v_add_f32_e32 v94, v94, v82
	s_waitcnt lgkmcnt(4)
	v_add_f32_e32 v78, v78, v66
	s_waitcnt lgkmcnt(3)
	v_add_f32_e32 v62, v62, v50
	s_waitcnt lgkmcnt(2)
	v_add_f32_e32 v46, v46, v34
	s_waitcnt lgkmcnt(1)
	v_add_f32_e32 v30, v30, v18
	s_waitcnt lgkmcnt(0)
	v_add_f32_e32 v14, v14, v2
	s_and_saveexec_b64 vcc, s[38:39]
	global_store_dword v218, v126, s[52:53]
	global_store_dword v218, v110, s[52:53] offset:2048
	s_add_u32 s54, s52, 0x1000
	s_addc_u32 s55, s53, 0
	global_store_dword v218, v94, s[54:55]
	s_add_u32 s54, s52, 0x1800
	s_addc_u32 s55, s53, 0
	global_store_dword v218, v78, s[54:55]
	s_add_u32 s54, s52, 0x4000
	s_addc_u32 s55, s53, 0
	global_store_dword v218, v62, s[54:55]
	s_add_u32 s54, s52, 0x4800
	s_addc_u32 s55, s53, 0
	global_store_dword v218, v46, s[54:55]
	s_add_u32 s54, s52, 0x5000
	s_addc_u32 s55, s53, 0
	global_store_dword v218, v30, s[54:55]
	s_add_u32 s54, s52, 0x5800
	s_addc_u32 s55, s53, 0
	global_store_dword v218, v14, s[54:55]
	s_mov_b64 exec, vcc
	s_mov_b64 s[52:53], exec
